# v23 + layer 0 scan phase: RG-LRU long-job workgroups convert 3072 more layer-1 w_in items after their job (team's loop, own range); branch-phase tail shortened accordingly
# speedup vs baseline: 1.0033x; 1.0033x over previous
.LBB0_80:
	v_readlane_b32 s22, v248, 1
	v_readlane_b32 s23, v248, 2
	s_add_u32 s0, s22, 0x72d00000
	s_addc_u32 s1, s23, 0
	v_writelane_b32 v249, s0, 4
	v_readlane_b32 s24, v248, 7
	v_readlane_b32 s48, v248, 26
	v_writelane_b32 v249, s1, 5
	s_ashr_i32 s0, s24, 31
	v_readlane_b32 s50, v248, 28
	v_writelane_b32 v249, s0, 6
	v_readlane_b32 s51, v248, 29
	s_add_u32 s0, s50, 0x2000
	s_addc_u32 s1, s51, 0
	v_writelane_b32 v249, s0, 7
	s_cmpk_lg_i32 s24, 0x100
	v_readlane_b32 s13, v248, 43
	v_writelane_b32 v249, s1, 8
	s_cselect_b64 s[0:1], -1, 0
	v_writelane_b32 v249, s0, 9
	s_cmpk_lt_i32 s13, 0x1400
	v_readlane_b32 s21, v248, 0
	v_writelane_b32 v249, s1, 10
	s_cselect_b64 s[0:1], -1, 0
	v_writelane_b32 v249, s0, 11
	v_readlane_b32 s49, v248, 27
	v_mov_b32_e32 v34, 0
	v_writelane_b32 v249, s1, 12
	s_add_i32 s0, s13, 0x3c80
	s_add_u32 s9, s22, 0x24500000
	s_addc_u32 s12, s23, 0
	s_add_u32 s5, s22, 0x1e500000
	v_writelane_b32 v249, s0, 13
	s_addc_u32 s11, s23, 0
	s_add_i32 s0, s21, 0xffffff97
	s_cmpk_lt_u32 s0, 0x67
	s_cselect_b64 s[0:1], -1, 0
	v_writelane_b32 v249, s0, 14
	v_mov_b32_e32 v219, 1
	v_mov_b32_e32 v222, 0x358637bd
	v_writelane_b32 v249, s1, 15
	s_add_i32 s0, s13, 0xfffffcb8
	s_cmpk_lt_i32 s0, 0x1400
	s_cselect_b64 s[0:1], -1, 0
	v_writelane_b32 v249, s0, 16
	v_mov_b32_e32 v223, 0x260
	v_mov_b32_e32 v224, 0x3ecc95a3
	v_writelane_b32 v249, s1, 17
	s_add_i32 s0, s13, 0x3938
	v_writelane_b32 v249, s0, 18
	s_add_u32 s0, s22, 0x4200
	s_addc_u32 s1, s23, 0
	v_writelane_b32 v249, s0, 19
	v_mov_b32_e32 v225, 0x3e2aaaab
	v_mov_b64_e32 v[164:165], 0x969
	v_writelane_b32 v249, s1, 20
	s_add_u32 s0, s22, 0x4400
	s_addc_u32 s1, s23, 0
	v_writelane_b32 v249, s0, 21
	v_mov_b64_e32 v[166:167], 0x968
	v_mov_b32_e32 v226, 0x41b17218
	v_writelane_b32 v249, s1, 22
	s_add_u32 s0, s22, 0x4500
	s_addc_u32 s1, s23, 0
	v_writelane_b32 v249, s0, 23
	v_mov_b64_e32 v[168:169], 0x630
	v_mov_b64_e32 v[170:171], 0x62f
	v_writelane_b32 v249, s1, 24
	s_add_u32 s0, s22, 0x4600
	s_addc_u32 s1, s23, 0
	v_writelane_b32 v249, s0, 25
	v_mov_b32_e32 v227, 0x1e040
	v_mov_b32_e32 v228, 2
	v_writelane_b32 v249, s1, 26
	s_add_u32 s0, s22, 0x4700
	s_addc_u32 s1, s23, 0
	v_writelane_b32 v249, s0, 27
	v_mov_b32_e32 v230, 0x3000
	v_mov_b32_e32 v231, 0x7f800000
	v_writelane_b32 v249, s1, 28
	s_add_u32 s0, s22, 0x4800
	s_addc_u32 s1, s23, 0
	v_writelane_b32 v249, s0, 29
	v_readlane_b32 s52, v248, 30
	v_readlane_b32 s53, v248, 31
	v_writelane_b32 v249, s1, 30
	s_add_u32 s0, s22, 0x4900
	s_addc_u32 s1, s23, 0
	v_writelane_b32 v249, s0, 31
	v_readlane_b32 s54, v248, 32
	v_readlane_b32 s55, v248, 33
	v_writelane_b32 v249, s1, 32
	s_add_u32 s0, s22, 0x4a00
	s_addc_u32 s1, s23, 0
	v_writelane_b32 v249, s0, 33
	v_readlane_b32 s56, v248, 34
	v_readlane_b32 s57, v248, 35
	v_writelane_b32 v249, s1, 34
	s_add_u32 s0, s22, 0x4b00
	s_addc_u32 s1, s23, 0
	v_writelane_b32 v249, s0, 35
	v_readlane_b32 s58, v248, 36
	v_readlane_b32 s59, v248, 37
	v_writelane_b32 v249, s1, 36
	s_add_u32 s0, s22, 0x4c00
	s_addc_u32 s1, s23, 0
	v_writelane_b32 v249, s0, 37
	v_readlane_b32 s60, v248, 38
	v_readlane_b32 s61, v248, 39
	v_writelane_b32 v249, s1, 38
	s_add_u32 s0, s22, 0x4d00
	s_addc_u32 s1, s23, 0
	v_writelane_b32 v249, s0, 39
	v_readlane_b32 s62, v248, 40
	v_readlane_b32 s63, v248, 41
	v_writelane_b32 v249, s1, 40
	s_add_u32 s0, s22, 0x4e00
	s_addc_u32 s1, s23, 0
	v_writelane_b32 v249, s0, 41
	s_nop 1
	v_writelane_b32 v249, s1, 42
	s_add_u32 s0, s22, 0x4f00
	s_addc_u32 s1, s23, 0
	v_writelane_b32 v249, s0, 43
	s_nop 1
	v_writelane_b32 v249, s1, 44
	s_add_u32 s0, s22, 0x5000
	s_addc_u32 s1, s23, 0
	v_writelane_b32 v249, s0, 45
	s_nop 1
	v_writelane_b32 v249, s1, 46
	s_add_u32 s0, s22, 0x5100
	s_addc_u32 s1, s23, 0
	v_writelane_b32 v249, s0, 47
	s_nop 1
	v_writelane_b32 v249, s1, 48
	s_add_u32 s0, s22, 0x5200
	s_addc_u32 s1, s23, 0
	v_writelane_b32 v249, s0, 49
	s_nop 1
	v_writelane_b32 v249, s1, 50
	s_add_u32 s0, s22, 0x5300
	s_addc_u32 s1, s23, 0
	v_writelane_b32 v249, s0, 51
	s_cmp_eq_u32 s46, 15
	s_nop 0
	v_writelane_b32 v249, s1, 52
	s_cselect_b64 s[0:1], -1, 0
	v_writelane_b32 v249, s0, 53
	s_cmp_eq_u32 s46, 14
	s_nop 0
	v_writelane_b32 v249, s1, 54
	s_cselect_b64 s[0:1], -1, 0
	v_writelane_b32 v249, s0, 55
	s_cmp_eq_u32 s46, 13
	s_nop 0
	v_writelane_b32 v249, s1, 56
	s_cselect_b64 s[0:1], -1, 0
	v_writelane_b32 v249, s0, 57
	s_cmp_eq_u32 s46, 12
	s_nop 0
	v_writelane_b32 v249, s1, 58
	s_cselect_b64 s[0:1], -1, 0
	v_writelane_b32 v249, s0, 59
	s_cmp_eq_u32 s46, 11
	s_nop 0
	v_writelane_b32 v249, s1, 60
	s_cselect_b64 s[0:1], -1, 0
	v_writelane_b32 v249, s0, 61
	s_cmp_eq_u32 s46, 10
	s_nop 0
	v_writelane_b32 v249, s1, 62
	s_cselect_b64 s[0:1], -1, 0
	v_writelane_b32 v249, s0, 63
	s_cmp_eq_u32 s46, 9
	s_nop 0
	v_writelane_b32 v250, s1, 0
	s_cselect_b64 s[0:1], -1, 0
	v_writelane_b32 v250, s0, 1
	s_cmp_eq_u32 s46, 8
	s_nop 0
	v_writelane_b32 v250, s1, 2
	s_cselect_b64 s[0:1], -1, 0
	v_writelane_b32 v250, s0, 3
	s_cmp_eq_u32 s46, 7
	s_nop 0
	v_writelane_b32 v250, s1, 4
	s_cselect_b64 s[0:1], -1, 0
	v_writelane_b32 v250, s0, 5
	s_cmp_eq_u32 s46, 6
	s_nop 0
	v_writelane_b32 v250, s1, 6
	s_cselect_b64 s[0:1], -1, 0
	v_writelane_b32 v250, s0, 7
	s_cmp_eq_u32 s46, 5
	s_nop 0
	v_writelane_b32 v250, s1, 8
	s_cselect_b64 s[0:1], -1, 0
	v_writelane_b32 v250, s0, 9
	s_cmp_eq_u32 s46, 4
	s_nop 0
	v_writelane_b32 v250, s1, 10
	s_cselect_b64 s[0:1], -1, 0
	v_writelane_b32 v250, s0, 11
	s_cmp_eq_u32 s46, 3
	s_nop 0
	v_writelane_b32 v250, s1, 12
	s_cselect_b64 s[0:1], -1, 0
	v_writelane_b32 v250, s0, 13
	s_cmp_eq_u32 s46, 2
	s_nop 0
	v_writelane_b32 v250, s1, 14
	s_cselect_b64 s[0:1], -1, 0
	v_writelane_b32 v250, s0, 15
	s_cmp_eq_u32 s46, 1
	s_nop 0
	v_writelane_b32 v250, s1, 16
	s_cselect_b64 s[0:1], -1, 0
	v_writelane_b32 v250, s0, 17
	s_cmp_eq_u32 s46, 0
	s_nop 0
	v_writelane_b32 v250, s1, 18
	s_cselect_b64 s[0:1], -1, 0
	v_writelane_b32 v250, s0, 19
	s_nop 1
	v_writelane_b32 v250, s1, 20
	s_lshl_b32 s0, s46, 8
	s_add_u32 s0, s2, s0
	s_addc_u32 s1, s3, 0
	s_add_u32 s2, s0, 0x1400
	s_addc_u32 s3, s1, 0
	v_writelane_b32 v250, s2, 21
	s_add_u32 s0, s0, 0x2400
	s_addc_u32 s1, s1, 0
	v_writelane_b32 v250, s3, 22
	v_writelane_b32 v250, s0, 23
	s_nop 1
	v_writelane_b32 v250, s1, 24
	s_add_u32 s0, s22, 0x7400
	s_addc_u32 s1, s23, 0
	v_writelane_b32 v250, s0, 25
	s_nop 1
	v_writelane_b32 v250, s1, 26
	s_add_u32 s0, s22, 0x7500
	s_addc_u32 s1, s23, 0
	v_writelane_b32 v250, s0, 27
	s_cmpk_lt_i32 s21, 0x220
	s_nop 0
	v_writelane_b32 v250, s1, 28
	s_cselect_b64 s[0:1], -1, 0
	v_writelane_b32 v250, s0, 29
	s_ashr_i32 s14, s21, 31
	s_add_i32 s8, s21, 0xffffff40
	v_writelane_b32 v250, s1, 30
	s_lshr_b32 s0, s14, 26
	s_add_i32 s0, s21, s0
	s_ashr_i32 s7, s0, 6
	s_add_i32 s0, s24, 0xffffff40
	v_writelane_b32 v250, s0, 31
	s_sub_i32 s0, s21, 64
	s_cmpk_lt_i32 s21, 0x80
	s_cselect_b32 s25, s21, s0
	s_add_i32 s25, s21, 0xffffff80
	s_cmpk_lt_i32 s21, 0x40
	s_cselect_b32 s25, s21, s25
	s_cmpk_lt_i32 s25, 0x220
	v_writelane_b32 v250, s0, 32
	s_cselect_b64 s[0:1], -1, 0
	v_writelane_b32 v250, s0, 33
	s_nop 1
	v_writelane_b32 v250, s1, 34
	s_add_u32 s0, s22, 0x12000
	v_writelane_b32 v250, s0, 35
	s_addc_u32 s0, s23, 0
	v_writelane_b32 v250, s0, 36
	s_add_i32 s0, s21, 0xffffff80
	v_writelane_b32 v250, s0, 37
	s_add_i32 s0, s21, 1
	v_writelane_b32 v250, s0, 38
	s_sub_i32 s0, s21, 63
	v_writelane_b32 v250, s0, 39
	s_add_i32 s0, s21, 0xffffff81
	s_cmpk_gt_i32 s21, 0xbf
	v_writelane_b32 v250, s0, 40
	s_cselect_b64 s[0:1], -1, 0
	s_cmpk_eq_i32 s24, 0x100
	s_cselect_b64 s[26:27], -1, 0
	s_and_b64 s[2:3], s[26:27], exec
	s_movk_i32 s2, 0x200
	s_cselect_b32 s6, s2, 0x210
	s_movk_i32 s2, 0x2000
	s_cselect_b32 s2, s2, 0x2100
	v_writelane_b32 v250, s2, 41
	s_cselect_b32 s19, 32, 33
	s_cselect_b32 s10, 0x1880, 0
	s_and_b64 s[0:1], s[0:1], s[26:27]
	v_writelane_b32 v250, s0, 42
	s_nop 1
	v_writelane_b32 v250, s1, 43
	s_add_u32 s0, s22, 0x10000
	v_writelane_b32 v250, s0, 44
	s_addc_u32 s0, s23, 0
	v_writelane_b32 v250, s0, 45
	s_lshl_b32 s0, s8, 3
	s_add_i32 s15, s33, s0
	s_cmpk_lt_i32 s21, 0xf0
	s_mul_hi_i32 s0, s8, 0x55555556
	s_cselect_b64 s[2:3], -1, 0
	s_lshr_b32 s1, s0, 31
	s_add_i32 s1, s0, s1
	s_mul_i32 s0, s1, -3
	v_writelane_b32 v250, s2, 46
	s_add_i32 s0, s0, s8
	s_mul_i32 s4, s1, 0x300000
	v_writelane_b32 v250, s3, 47
	s_lshl_b32 s2, s0, 11
	s_ashr_i32 s3, s2, 31
	s_lshl_b64 s[28:29], s[2:3], 1
	s_add_u32 s2, s5, s28
	v_writelane_b32 v250, s5, 48
	s_addc_u32 s3, s11, s29
	v_writelane_b32 v250, s11, 49
	s_add_u32 s2, s2, s4
	s_mul_hi_i32 s5, s1, 0x300000
	v_writelane_b32 v250, s2, 50
	s_addc_u32 s2, s3, s5
	v_writelane_b32 v250, s2, 51
	s_lshl_b32 s1, s1, 8
	v_writelane_b32 v250, s1, 52
	s_ashr_i32 s1, s0, 31
	s_lshl_b64 s[2:3], s[0:1], 12
	v_writelane_b32 v250, s2, 53
	s_lshl_b64 s[0:1], s[0:1], 22
	s_ashr_i32 s8, s8, 2
	v_writelane_b32 v250, s3, 54
	v_writelane_b32 v250, s0, 55
	s_nop 1
	v_writelane_b32 v250, s1, 56
	s_and_b32 s0, s21, 3
	s_lshl_b32 s2, s0, 10
	s_lshl_b32 s30, s0, 11
	v_writelane_b32 v250, s9, 57
	s_add_u32 s11, s9, s30
	v_writelane_b32 v250, s12, 58
	s_addc_u32 s12, s12, 0
	s_ashr_i32 s9, s8, 31
	s_lshl_b32 s3, s0, 20
	s_lshl_b64 s[0:1], s[8:9], 21
	s_add_u32 s9, s11, s0
	v_writelane_b32 v250, s9, 59
	s_addc_u32 s9, s12, s1
	v_writelane_b32 v250, s9, 60
	s_lshl_b32 s8, s8, 8
	v_writelane_b32 v250, s8, 61
	s_cmpk_lt_i32 s15, 0xc80
	v_writelane_b32 v250, s15, 62
	s_cselect_b64 s[8:9], -1, 0
	v_writelane_b32 v250, s8, 63
	s_nop 1
	v_writelane_b32 v251, s9, 0
	s_add_u32 s8, s48, 0x1e040000
	s_addc_u32 s9, s49, 0
	v_writelane_b32 v251, s8, 1
	v_readlane_b32 s36, v248, 10
	v_readlane_b32 s50, v248, 24
	v_writelane_b32 v251, s9, 2
	s_add_u32 s8, s22, 0xf300000
	s_addc_u32 s9, s23, 0
	s_lshl_b32 s34, s19, 4
	v_writelane_b32 v251, s8, 3
	s_cmp_lt_i32 s21, s34
	v_readlane_b32 s51, v248, 25
	v_writelane_b32 v251, s9, 4
	s_cselect_b64 s[8:9], -1, 0
	v_writelane_b32 v251, s8, 5
	s_add_i32 s16, s24, s6
	s_add_i32 s20, s19, -8
	v_writelane_b32 v251, s9, 6
	s_lshr_b32 s8, s14, 29
	s_add_i32 s8, s21, s8
	v_writelane_b32 v251, s14, 7
	s_ashr_i32 s14, s8, 3
	s_and_b32 s8, s8, -8
	s_sub_i32 s15, s21, s8
	s_add_i32 s17, s16, -1
	s_add_i32 s8, s13, s10
	s_cmpk_lt_i32 s8, 0x3c80
	v_writelane_b32 v251, s8, 8
	s_cselect_b64 s[8:9], -1, 0
	v_writelane_b32 v251, s8, 9
	v_readlane_b32 s48, v248, 22
	v_readlane_b32 s49, v248, 23
	v_writelane_b32 v251, s9, 10
	s_add_u32 s8, s22, 0x85300000
	s_addc_u32 s9, s23, 0
	s_lshl_b32 s31, s19, 1
	v_writelane_b32 v251, s8, 11
	s_add_i32 s18, s10, s33
	s_or_b32 s33, s31, 1
	v_writelane_b32 v251, s9, 12
	s_add_u32 s8, s22, 0x76d00000
	v_writelane_b32 v251, s8, 13
	s_addc_u32 s8, s23, 0
	v_writelane_b32 v251, s8, 14
	s_add_u32 s8, s50, 0x4000
	s_addc_u32 s9, s51, 0
	v_writelane_b32 v251, s8, 15
	v_mov_b32_e32 v1, s15
	v_alignbit_b32 v1, s19, v1, 31
	v_writelane_b32 v251, s9, 16
	s_add_u32 s8, s48, 0x4000
	s_addc_u32 s9, s49, 0
	v_writelane_b32 v251, s8, 17
	v_readlane_b32 s37, v248, 11
	v_readlane_b32 s38, v248, 12
	v_writelane_b32 v251, s9, 18
	v_readlane_b32 s8, v248, 3
	v_readlane_b32 s9, v248, 4
	s_mov_b64 s[12:13], s[8:9]
	s_cmp_gt_i32 s12, 7
	v_readlane_b32 s10, v248, 5
	v_readlane_b32 s11, v248, 6
	s_cselect_b64 s[8:9], -1, 0
	s_cmp_lt_i32 s13, 9
	s_cselect_b64 s[10:11], -1, 0
	s_cmpk_lt_i32 s21, 0xc0
	s_cselect_b32 s7, s7, -1
	s_cmpk_gt_i32 s24, 0xc0
	s_cselect_b32 s7, s7, -2
	s_cmp_lt_i32 s7, 1
	s_cselect_b64 s[12:13], -1, 0
	v_writelane_b32 v251, s26, 19
	s_and_b64 s[12:13], s[26:27], s[12:13]
	s_cmp_lg_u32 s7, 1
	v_writelane_b32 v251, s27, 20
	v_writelane_b32 v251, s12, 21
	v_readlane_b32 s39, v248, 13
	v_readlane_b32 s40, v248, 14
	v_writelane_b32 v251, s13, 22
	v_writelane_b32 v251, s7, 23
	v_readfirstlane_b32 s7, v1
	v_writelane_b32 v251, s19, 24
	s_mul_i32 s7, s7, s15
	s_cselect_b64 s[12:13], -1, 0
	v_writelane_b32 v251, s12, 25
	s_add_i32 s7, s7, s14
	v_readlane_b32 s41, v248, 15
	v_writelane_b32 v251, s13, 26
	s_ashr_i32 s12, s7, 31
	s_lshr_b32 s12, s12, 25
	s_add_i32 s12, s7, s12
	s_ashr_i32 s12, s12, 7
	s_lshl_b32 s13, s12, 7
	s_sub_i32 s7, s7, s13
	s_lshl_b32 s12, s12, 3
	s_cmp_gt_i32 s12, s20
	s_cselect_b32 s13, 1, 8
	s_cmp_lt_i32 s15, 0
	s_cselect_b32 s19, s33, s31
	s_mul_i32 s15, s19, s15
	s_add_i32 s14, s15, s14
	v_cvt_f32_ubyte0_e32 v1, s13
	s_ashr_i32 s15, s14, 31
	v_rcp_iflag_f32_e32 v1, v1
	s_lshr_b32 s15, s15, 25
	s_add_i32 s15, s14, s15
	s_ashr_i32 s15, s15, 7
	s_lshl_b32 s19, s15, 7
	v_mul_f32_e32 v1, 0x4f7ffffe, v1
	v_writelane_b32 v251, s31, 27
	s_sub_i32 s14, s14, s19
	s_lshl_b32 s15, s15, 3
	v_cvt_u32_f32_e32 v1, v1
	v_writelane_b32 v251, s33, 28
	s_cmp_gt_i32 s15, s20
	v_writelane_b32 v251, s20, 29
	s_cselect_b32 s19, 1, 8
	s_or_b64 s[8:9], s[8:9], s[10:11]
	v_writelane_b32 v251, s8, 30
	s_mov_b32 s33, 0xbcf5c28f
	v_readlane_b32 s42, v248, 16
	v_writelane_b32 v251, s9, 31
	s_sub_i32 s8, 0, s13
	v_readfirstlane_b32 s9, v1
	s_mul_i32 s8, s8, s9
	s_mul_hi_u32 s8, s9, s8
	s_add_i32 s9, s9, s8
	s_abs_i32 s8, s7
	s_mul_hi_u32 s9, s8, s9
	s_mul_i32 s10, s9, s13
	s_sub_i32 s8, s8, s10
	s_ashr_i32 s10, s7, 31
	s_add_i32 s11, s9, 1
	s_sub_i32 s20, s8, s13
	s_cmp_ge_u32 s8, s13
	s_cselect_b32 s9, s11, s9
	s_cselect_b32 s8, s20, s8
	s_add_i32 s11, s9, 1
	s_cmp_ge_u32 s8, s13
	s_cselect_b32 s8, s11, s9
	s_xor_b32 s8, s8, s10
	s_sub_i32 s8, s8, s10
	v_writelane_b32 v251, s8, 32
	s_mul_i32 s8, s8, s13
	s_sub_i32 s7, s7, s8
	s_add_i32 s7, s12, s7
	v_writelane_b32 v251, s7, 33
	s_abs_i32 s7, s24
	v_cvt_f32_u32_e32 v1, s7
	s_sub_i32 s8, 0, s7
	v_readlane_b32 s43, v248, 17
	v_readlane_b32 s44, v248, 18
	v_rcp_iflag_f32_e32 v1, v1
	v_readlane_b32 s45, v248, 19
	v_readlane_b32 s46, v248, 20
	v_readlane_b32 s47, v248, 21
	v_mul_f32_e32 v1, 0x4f7ffffe, v1
	v_cvt_u32_f32_e32 v1, v1
	s_nop 0
	v_readfirstlane_b32 s9, v1
	s_mul_i32 s8, s8, s9
	s_mul_hi_u32 s8, s9, s8
	s_add_i32 s9, s9, s8
	s_sub_i32 s8, 1, s16
	s_max_i32 s8, s17, s8
	s_mul_hi_u32 s9, s8, s9
	s_mul_i32 s10, s9, s7
	s_sub_i32 s8, s8, s10
	s_xor_b32 s10, s17, s24
	s_ashr_i32 s10, s10, 31
	s_add_i32 s11, s9, 1
	s_sub_i32 s12, s8, s7
	s_cmp_ge_u32 s8, s7
	s_cselect_b32 s9, s11, s9
	s_cselect_b32 s8, s12, s8
	s_add_i32 s11, s9, 1
	s_cmp_ge_u32 s8, s7
	s_cselect_b32 s7, s11, s9
	s_xor_b32 s7, s7, s10
	s_not_b32 s8, s10
	s_add_i32 s7, s8, s7
	s_mul_i32 s7, s7, s24
	s_sub_i32 s6, s6, s7
	s_sub_i32 s7, s24, s6
	v_cvt_f32_ubyte0_e32 v1, s19
	s_cmp_lt_i32 s7, 1
	v_rcp_iflag_f32_e32 v1, v1
	s_cselect_b64 s[8:9], -1, 0
	v_writelane_b32 v251, s8, 34
	s_cmp_ge_i32 s21, s6
	v_mul_f32_e32 v1, 0x4f7ffffe, v1
	v_writelane_b32 v251, s9, 35
	s_cselect_b64 s[8:9], -1, 0
	s_sub_i32 s6, s21, s6
	v_writelane_b32 v251, s8, 36
	s_lshl_b32 s6, s6, 3
	s_add_i32 s6, s18, s6
	v_writelane_b32 v251, s9, 37
	s_lshl_b32 s7, s7, 3
	v_cvt_u32_f32_e32 v1, v1
	v_writelane_b32 v251, s7, 38
	s_cmpk_lt_i32 s6, 0x3c80
	v_writelane_b32 v251, s6, 39
	s_cselect_b64 s[6:7], -1, 0
	v_writelane_b32 v251, s6, 40
	s_nop 1
	v_writelane_b32 v251, s7, 41
	s_sub_i32 s6, 0, s19
	v_readfirstlane_b32 s7, v1
	s_mul_i32 s6, s6, s7
	s_mul_hi_u32 s6, s7, s6
	s_add_i32 s7, s7, s6
	s_abs_i32 s6, s14
	s_mul_hi_u32 s7, s6, s7
	s_mul_i32 s8, s7, s19
	s_sub_i32 s6, s6, s8
	s_ashr_i32 s8, s14, 31
	s_add_i32 s9, s7, 1
	s_sub_i32 s10, s6, s19
	s_cmp_ge_u32 s6, s19
	s_cselect_b32 s7, s9, s7
	s_cselect_b32 s6, s10, s6
	s_add_i32 s9, s7, 1
	s_cmp_ge_u32 s6, s19
	s_cselect_b32 s6, s9, s7
	s_xor_b32 s6, s6, s8
	s_sub_i32 s8, s6, s8
	s_mul_i32 s6, s8, s19
	s_sub_i32 s6, s14, s6
	s_add_i32 s10, s15, s6
	s_lshl_b32 s6, s21, 8
	v_writelane_b32 v251, s6, 42
	s_lshl_b32 s6, s24, 8
	v_writelane_b32 v251, s6, 43
	v_writelane_b32 v251, s25, 44
	s_lshl_b32 s6, s25, 8
	v_writelane_b32 v251, s6, 45
	s_mov_b32 s6, s10
	s_ashr_i32 s11, s10, 31
	v_writelane_b32 v251, s6, 46
	s_ashr_i32 s9, s8, 31
	v_mbcnt_lo_u32_b32 v1, -1, 0
	v_writelane_b32 v251, s7, 47
	s_lshl_b64 s[6:7], s[10:11], 21
	v_writelane_b32 v251, s6, 48
	v_mbcnt_hi_u32_b32 v229, -1, v1
	s_nop 0
	v_writelane_b32 v251, s7, 49
	s_mov_b32 s6, s8
	v_writelane_b32 v251, s6, 50
	s_nop 1
	v_writelane_b32 v251, s7, 51
	s_lshl_b64 s[6:7], s[8:9], 21
	s_add_u32 s4, s4, s28
	s_addc_u32 s5, s5, s29
	s_add_u32 s4, s22, s4
	v_writelane_b32 v251, s6, 52
	s_addc_u32 s5, s23, s5
	s_add_u32 s4, s4, 0x1e500100
	v_writelane_b32 v251, s7, 53
	v_writelane_b32 v251, s4, 54
	s_addc_u32 s4, s5, 0
	v_writelane_b32 v251, s4, 55
	s_add_u32 s4, s28, 0x55b80080
	v_writelane_b32 v251, s4, 56
	v_writelane_b32 v251, s28, 57
	s_addc_u32 s4, s29, 0
	s_or_b32 s0, s0, s30
	v_writelane_b32 v251, s29, 58
	s_mov_b32 s5, 0
	v_writelane_b32 v251, s4, 59
	s_add_u32 s0, s22, s0
	s_mov_b32 s35, s5
	s_addc_u32 s1, s23, s1
	v_writelane_b32 v251, s34, 60
	s_add_u32 s0, s0, 0x24500100
	s_mov_b64 s[6:7], -1
	v_writelane_b32 v251, s35, 61
	v_writelane_b32 v251, s0, 62
	s_addc_u32 s0, s1, 0
	v_writelane_b32 v251, s0, 63
	s_mul_hi_i32 s1, s66, 0x3000
	s_mul_i32 s0, s66, 0x3000
	v_writelane_b32 v252, s0, 0
	s_ashr_i32 s67, s66, 31
	s_mov_b32 s12, s5
	v_writelane_b32 v252, s1, 1
	s_lshl_b32 s0, s2, 1
	v_writelane_b32 v252, s0, 2
	s_lshl_b32 s0, s3, 2
	v_writelane_b32 v252, s0, 3
	v_writelane_b32 v252, s30, 4
	s_or_b32 s0, s30, 0x6a800080
	v_writelane_b32 v252, s0, 5
	s_add_i32 s0, 0, 0x19800
	v_writelane_b32 v252, s0, 6
	v_cmp_eq_u32_e64 s[0:1], 0, v0
	s_mov_b64 s[2:3], 0x80
	s_nop 0
	v_writelane_b32 v252, s0, 7
	s_nop 1
	v_writelane_b32 v252, s1, 8
	s_lshl_b64 s[0:1], s[66:67], 12
	v_writelane_b32 v252, s0, 9
	s_nop 1
	v_writelane_b32 v252, s1, 10
	s_lshl_b64 s[0:1], s[66:67], 7
	v_writelane_b32 v252, s0, 11
	s_nop 1
	v_writelane_b32 v252, s1, 12
	s_lshl_b64 s[0:1], s[66:67], 13
	v_writelane_b32 v252, s0, 13
	s_nop 1
	v_writelane_b32 v252, s1, 14
	s_mov_b32 s1, 0
	v_writelane_b32 v252, s0, 15
	s_nop 1
	v_writelane_b32 v252, s1, 16
	v_writelane_b32 v252, s66, 17
	s_nop 1
	v_writelane_b32 v252, s67, 18
	s_branch .LBB0_84

.LBB0_1494:
	v_readlane_b32 s0, v252, 3
	v_readlane_b32 s4, v252, 37
	v_readlane_b32 s5, v252, 38
	s_add_u32 s0, s4, s0
	s_addc_u32 s1, s5, 0
	s_add_u32 s0, s0, 0x73d00000
	s_addc_u32 s1, s1, 0
	s_addk_i32 s18, 0x2000
	v_readlane_b32 s4, v250, 61
	v_or_b32_e32 v132, s18, v35
	s_or_b32 s4, s19, s4
	v_or_b32_e32 v134, s4, v144
	v_ashrrev_i32_e32 v133, 31, v132
	v_ashrrev_i32_e32 v135, 31, v134
	v_lshlrev_b64 v[136:137], 14, v[132:133]
	v_lshl_add_u64 v[136:137], s[0:1], 0, v[136:137]
	v_lshlrev_b64 v[134:135], 2, v[134:135]
	v_lshl_add_u64 v[136:137], v[136:137], 0, v[134:135]
	s_barrier
	flat_store_dwordx4 v[136:137], v[128:131]
	flat_store_dwordx4 v[136:137], v[124:127] offset:16
	flat_store_dwordx4 v[136:137], v[112:115] offset:512
	flat_store_dwordx4 v[136:137], v[104:107] offset:528
	s_nop 1
	v_or_b32_e32 v104, 16, v132
	v_ashrrev_i32_e32 v105, 31, v104
	v_lshlrev_b64 v[104:105], 14, v[104:105]
	v_lshl_add_u64 v[104:105], s[0:1], 0, v[104:105]
	v_lshl_add_u64 v[104:105], v[104:105], 0, v[134:135]
	flat_store_dwordx4 v[104:105], v[120:123]
	flat_store_dwordx4 v[104:105], v[116:119] offset:16
	flat_store_dwordx4 v[104:105], v[96:99] offset:512
	flat_store_dwordx4 v[104:105], v[88:91] offset:528
	s_nop 1
	v_or_b32_e32 v88, 32, v132
	v_ashrrev_i32_e32 v89, 31, v88
	v_lshlrev_b64 v[88:89], 14, v[88:89]
	v_lshl_add_u64 v[88:89], s[0:1], 0, v[88:89]
	v_lshl_add_u64 v[88:89], v[88:89], 0, v[134:135]
	flat_store_dwordx4 v[88:89], v[108:111]
	flat_store_dwordx4 v[88:89], v[100:103] offset:16
	flat_store_dwordx4 v[88:89], v[80:83] offset:512
	flat_store_dwordx4 v[88:89], v[76:79] offset:528
	s_nop 1
	v_or_b32_e32 v76, 48, v132
	v_ashrrev_i32_e32 v77, 31, v76
	v_lshlrev_b64 v[76:77], 14, v[76:77]
	v_lshl_add_u64 v[76:77], s[0:1], 0, v[76:77]
	v_lshl_add_u64 v[76:77], v[76:77], 0, v[134:135]
	s_mov_b32 s0, 0x200000
	flat_store_dwordx4 v[76:77], v[92:95]
	flat_store_dwordx4 v[76:77], v[84:87] offset:16
	flat_store_dwordx4 v[76:77], v[72:75] offset:512
	flat_store_dwordx4 v[76:77], v[68:71] offset:528
	s_nop 1
	v_add_co_u32_e32 v70, vcc, s0, v136
	s_mov_b64 s[0:1], 0x240000
	s_nop 0
	v_addc_co_u32_e32 v71, vcc, 0, v137, vcc
	v_lshl_add_u64 v[68:69], v[136:137], 0, s[30:31]
	flat_store_dwordx4 v[70:71], v[64:67]
	flat_store_dwordx4 v[68:69], v[60:63] offset:16
	flat_store_dwordx4 v[68:69], v[48:51] offset:512
	flat_store_dwordx4 v[68:69], v[44:47] offset:528
	s_nop 1
	v_lshl_add_u64 v[44:45], v[136:137], 0, s[0:1]
	s_mov_b32 s0, 0x240000
	v_add_co_u32_e32 v46, vcc, s0, v136
	s_mov_b64 s[0:1], 0x280000
	s_nop 0
	v_addc_co_u32_e32 v47, vcc, 0, v137, vcc
	flat_store_dwordx4 v[46:47], v[56:59]
	flat_store_dwordx4 v[44:45], v[52:55] offset:16
	flat_store_dwordx4 v[44:45], v[30:33] offset:512
	flat_store_dwordx4 v[44:45], v[26:29] offset:528
	s_nop 1
	v_lshl_add_u64 v[26:27], v[136:137], 0, s[0:1]
	s_mov_b32 s0, 0x280000
	v_add_co_u32_e32 v28, vcc, s0, v136
	s_mov_b64 s[0:1], 0x2c0000
	s_nop 0
	v_addc_co_u32_e32 v29, vcc, 0, v137, vcc
	flat_store_dwordx4 v[28:29], v[40:43]
	flat_store_dwordx4 v[26:27], v[36:39] offset:16
	flat_store_dwordx4 v[26:27], v[14:17] offset:512
	flat_store_dwordx4 v[26:27], v[10:13] offset:528
	s_nop 1
	v_lshl_add_u64 v[10:11], v[136:137], 0, s[0:1]
	v_add_co_u32_e32 v12, vcc, 0x2c0000, v136
	v_readlane_b32 s0, v252, 19
	s_nop 0
	v_addc_co_u32_e32 v13, vcc, 0, v137, vcc
	v_readlane_b32 s1, v252, 20
	s_andn2_b64 vcc, exec, s[0:1]
	flat_store_dwordx4 v[12:13], v[22:25]
	flat_store_dwordx4 v[10:11], v[18:21] offset:16
	flat_store_dwordx4 v[10:11], v[6:9] offset:512
	flat_store_dwordx4 v[10:11], v[2:5] offset:528
	s_cbranch_vccnz .LBB0_1506
	v_readlane_b32 s0, v250, 63
	v_readlane_b32 s1, v251, 0
	v_and_b32_e32 v2, 63, v0
	s_andn2_b64 vcc, exec, s[0:1]
	s_cbranch_vccnz .LBB0_1506
	s_movk_i32 s99, 0xa80
	v_lshlrev_b32_e32 v1, 3, v2
	v_and_b32_e32 v4, 56, v1
	v_readlane_b32 s7, v250, 62
	v_lshlrev_b32_e32 v35, 1, v2
	v_lshlrev_b32_e32 v134, 8, v2
	v_ashrrev_i32_e32 v135, 3, v2
	v_lshlrev_b32_e32 v136, 4, v2
	s_lshl_b32 s6, s7, 7
	v_lshlrev_b32_e32 v2, 1, v4
	s_branch .LBB0_1498
.LBB0_1497:
	s_or_b64 exec, exec, s[4:5]
	v_readfirstlane_b32 s4, v0
	s_lshl_b32 s4, s4, 8
	s_and_b32 s4, s4, 0x7fffc000
	s_add_i32 s4, s4, 0
	v_add_u32_e32 v1, s4, v134
	s_waitcnt vmcnt(0)
	v_cvt_pk_bf16_f32 v139, v6, v4
	v_cvt_pk_bf16_f32 v4, v11, v9
	v_cvt_pk_bf16_f32 v5, v7, v5
	v_cvt_pk_bf16_f32 v6, v25, v21
	v_cvt_pk_bf16_f32 v7, v17, v13
	ds_write_b128 v1, v[4:7] offset:128
	v_cvt_pk_bf16_f32 v4, v27, v23
	v_cvt_pk_bf16_f32 v5, v19, v15
	v_cvt_pk_bf16_f32 v6, v43, v39
	v_cvt_pk_bf16_f32 v7, v33, v29
	v_cvt_pk_bf16_f32 v138, v10, v8
	v_cvt_pk_bf16_f32 v140, v24, v20
	v_cvt_pk_bf16_f32 v141, v16, v12
	ds_write_b128 v1, v[4:7] offset:144
	v_cvt_pk_bf16_f32 v4, v45, v41
	v_cvt_pk_bf16_f32 v5, v37, v31
	v_cvt_pk_bf16_f32 v6, v59, v55
	v_cvt_pk_bf16_f32 v7, v51, v47
	ds_write_b128 v1, v[138:141]
	v_cvt_pk_bf16_f32 v138, v26, v22
	v_cvt_pk_bf16_f32 v139, v18, v14
	v_cvt_pk_bf16_f32 v140, v42, v38
	v_cvt_pk_bf16_f32 v141, v32, v28
	ds_write_b128 v1, v[4:7] offset:160
	v_cvt_pk_bf16_f32 v4, v61, v57
	v_cvt_pk_bf16_f32 v5, v53, v49
	v_cvt_pk_bf16_f32 v6, v75, v71
	v_cvt_pk_bf16_f32 v7, v67, v63
	ds_write_b128 v1, v[138:141] offset:16
	v_cvt_pk_bf16_f32 v138, v44, v40
	v_cvt_pk_bf16_f32 v139, v36, v30
	v_cvt_pk_bf16_f32 v140, v58, v54
	v_cvt_pk_bf16_f32 v141, v50, v46
	ds_write_b128 v1, v[4:7] offset:176
	v_cvt_pk_bf16_f32 v4, v77, v73
	v_cvt_pk_bf16_f32 v5, v69, v65
	v_cvt_pk_bf16_f32 v6, v91, v87
	v_cvt_pk_bf16_f32 v7, v83, v79
	ds_write_b128 v1, v[138:141] offset:32
	v_cvt_pk_bf16_f32 v138, v60, v56
	v_cvt_pk_bf16_f32 v139, v52, v48
	v_cvt_pk_bf16_f32 v140, v74, v70
	v_cvt_pk_bf16_f32 v141, v66, v62
	ds_write_b128 v1, v[4:7] offset:192
	v_cvt_pk_bf16_f32 v4, v93, v89
	v_cvt_pk_bf16_f32 v5, v85, v81
	v_cvt_pk_bf16_f32 v6, v107, v103
	v_cvt_pk_bf16_f32 v7, v99, v95
	ds_write_b128 v1, v[138:141] offset:48
	v_cvt_pk_bf16_f32 v138, v76, v72
	v_cvt_pk_bf16_f32 v139, v68, v64
	v_cvt_pk_bf16_f32 v140, v90, v86
	v_cvt_pk_bf16_f32 v141, v82, v78
	ds_write_b128 v1, v[4:7] offset:208
	v_cvt_pk_bf16_f32 v4, v109, v105
	v_cvt_pk_bf16_f32 v5, v101, v97
	v_cvt_pk_bf16_f32 v6, v123, v119
	v_cvt_pk_bf16_f32 v7, v115, v111
	ds_write_b128 v1, v[138:141] offset:64
	v_cvt_pk_bf16_f32 v138, v92, v88
	v_cvt_pk_bf16_f32 v139, v84, v80
	v_cvt_pk_bf16_f32 v140, v106, v102
	v_cvt_pk_bf16_f32 v141, v98, v94
	ds_write_b128 v1, v[4:7] offset:224
	v_cvt_pk_bf16_f32 v4, v125, v121
	v_cvt_pk_bf16_f32 v5, v117, v113
	v_cvt_pk_bf16_f32 v6, v133, v131
	v_cvt_pk_bf16_f32 v7, v129, v127
	ds_write_b128 v1, v[138:141] offset:80
	v_cvt_pk_bf16_f32 v138, v108, v104
	v_cvt_pk_bf16_f32 v139, v100, v96
	v_cvt_pk_bf16_f32 v140, v122, v118
	v_cvt_pk_bf16_f32 v141, v114, v110
	ds_write_b128 v1, v[4:7] offset:240
	v_add_u32_e32 v4, s8, v135
	ds_write_b128 v1, v[138:141] offset:96
	v_cvt_pk_bf16_f32 v138, v124, v120
	v_cvt_pk_bf16_f32 v139, v116, v112
	v_cvt_pk_bf16_f32 v140, v132, v130
	v_cvt_pk_bf16_f32 v141, v128, v126
	v_ashrrev_i32_e32 v5, 31, v4
	v_readlane_b32 s8, v251, 3
	ds_write_b128 v1, v[138:141] offset:112
	v_lshlrev_b64 v[4:5], 13, v[4:5]
	v_readlane_b32 s9, v251, 4
	v_add_u32_e32 v1, s4, v136
	v_mov_b32_e32 v3, v34
	v_lshl_add_u64 v[8:9], s[8:9], 0, v[4:5]
	ds_read_b128 v[4:7], v1
	v_lshl_add_u64 v[8:9], s[0:1], 1, v[8:9]
	v_lshl_add_u64 v[12:13], v[8:9], 0, v[2:3]
	ds_read_b128 v[8:11], v1 offset:1024
	s_mov_b32 s0, 0x10000
	s_waitcnt lgkmcnt(0)
	global_store_dwordx4 v[12:13], v[4:7], off
	s_add_i32 s6, s6, 0x10000
	s_nop 0
	v_add_co_u32_e32 v4, vcc, s0, v12
	s_mov_b32 s0, 0x20000
	s_nop 0
	v_addc_co_u32_e32 v5, vcc, 0, v13, vcc
	global_store_dwordx4 v[4:5], v[8:11], off
	ds_read_b128 v[4:7], v1 offset:2048
	ds_read_b128 v[8:11], v1 offset:3072
	v_add_co_u32_e32 v14, vcc, s0, v12
	s_mov_b32 s0, 0x30000
	s_nop 0
	v_addc_co_u32_e32 v15, vcc, 0, v13, vcc
	s_waitcnt lgkmcnt(1)
	global_store_dwordx4 v[14:15], v[4:7], off
	s_nop 1
	v_add_co_u32_e32 v4, vcc, s0, v12
	s_mov_b32 s0, 0x40000
	s_nop 0
	v_addc_co_u32_e32 v5, vcc, 0, v13, vcc
	s_waitcnt lgkmcnt(0)
	global_store_dwordx4 v[4:5], v[8:11], off
	ds_read_b128 v[4:7], v1 offset:4096
	ds_read_b128 v[8:11], v1 offset:5120
	v_add_co_u32_e32 v14, vcc, s0, v12
	s_mov_b32 s0, 0x50000
	s_nop 0
	v_addc_co_u32_e32 v15, vcc, 0, v13, vcc
	s_waitcnt lgkmcnt(1)
	global_store_dwordx4 v[14:15], v[4:7], off
	s_nop 1
	v_add_co_u32_e32 v4, vcc, s0, v12
	s_mov_b32 s0, 0x60000
	s_nop 0
	v_addc_co_u32_e32 v5, vcc, 0, v13, vcc
	s_waitcnt lgkmcnt(0)
	global_store_dwordx4 v[4:5], v[8:11], off
	ds_read_b128 v[4:7], v1 offset:6144
	ds_read_b128 v[8:11], v1 offset:7168
	v_add_co_u32_e32 v14, vcc, s0, v12
	s_mov_b32 s0, 0x70000
	s_nop 0
	v_addc_co_u32_e32 v15, vcc, 0, v13, vcc
	s_waitcnt lgkmcnt(1)
	global_store_dwordx4 v[14:15], v[4:7], off
	s_nop 1
	v_add_co_u32_e32 v4, vcc, s0, v12
	s_mov_b32 s0, 0x80000
	s_nop 0
	v_addc_co_u32_e32 v5, vcc, 0, v13, vcc
	s_waitcnt lgkmcnt(0)
	global_store_dwordx4 v[4:5], v[8:11], off
	ds_read_b128 v[4:7], v1 offset:8192
	ds_read_b128 v[8:11], v1 offset:9216
	v_add_co_u32_e32 v14, vcc, s0, v12
	s_mov_b32 s0, 0x90000
	s_nop 0
	v_addc_co_u32_e32 v15, vcc, 0, v13, vcc
	s_waitcnt lgkmcnt(1)
	global_store_dwordx4 v[14:15], v[4:7], off
	s_nop 1
	v_add_co_u32_e32 v4, vcc, s0, v12
	s_mov_b32 s0, 0xa0000
	s_nop 0
	v_addc_co_u32_e32 v5, vcc, 0, v13, vcc
	s_waitcnt lgkmcnt(0)
	global_store_dwordx4 v[4:5], v[8:11], off
	ds_read_b128 v[4:7], v1 offset:10240
	ds_read_b128 v[8:11], v1 offset:11264
	v_add_co_u32_e32 v14, vcc, s0, v12
	s_mov_b32 s0, 0xb0000
	s_nop 0
	v_addc_co_u32_e32 v15, vcc, 0, v13, vcc
	s_waitcnt lgkmcnt(1)
	global_store_dwordx4 v[14:15], v[4:7], off
	s_nop 1
	v_add_co_u32_e32 v4, vcc, s0, v12
	s_mov_b32 s0, 0xc0000
	s_nop 0
	v_addc_co_u32_e32 v5, vcc, 0, v13, vcc
	s_waitcnt lgkmcnt(0)
	global_store_dwordx4 v[4:5], v[8:11], off
	ds_read_b128 v[4:7], v1 offset:12288
	ds_read_b128 v[8:11], v1 offset:13312
	v_add_co_u32_e32 v14, vcc, s0, v12
	s_mov_b32 s0, 0xd0000
	s_nop 0
	v_addc_co_u32_e32 v15, vcc, 0, v13, vcc
	s_waitcnt lgkmcnt(1)
	global_store_dwordx4 v[14:15], v[4:7], off
	s_nop 1
	v_add_co_u32_e32 v4, vcc, s0, v12
	s_add_i32 s0, s7, 0x200
	s_nop 0
	v_addc_co_u32_e32 v5, vcc, 0, v13, vcc
	s_waitcnt lgkmcnt(0)
	global_store_dwordx4 v[4:5], v[8:11], off
	ds_read_b128 v[4:7], v1 offset:14336
	ds_read_b128 v[8:11], v1 offset:15360
	v_add_co_u32_e32 v14, vcc, 0xe0000, v12
	s_cmp_lt_i32 s7, s99
	s_nop 0
	v_addc_co_u32_e32 v15, vcc, 0, v13, vcc
	s_waitcnt lgkmcnt(1)
	global_store_dwordx4 v[14:15], v[4:7], off
	s_mov_b32 s7, s0
	s_nop 0
	v_add_co_u32_e32 v4, vcc, 0xf0000, v12
	s_nop 1
	v_addc_co_u32_e32 v5, vcc, 0, v13, vcc
	s_waitcnt lgkmcnt(0)
	global_store_dwordx4 v[4:5], v[8:11], off
	s_cbranch_scc0 .LBB0_1506

.Llru_cv:
	v_readlane_b32 s0, v251, 23
	v_readlane_b32 s1, v252, 27
	v_readlane_b32 s7, v248, 0
	v_readfirstlane_b32 s4, v0
	s_nop 3
	s_cmp_lg_u32 s0, 2
	s_cbranch_scc1 .LBB0_1506
	s_cmp_lg_u32 s1, 0
	s_cbranch_scc1 .LBB0_1506
	s_lshr_b32 s4, s4, 6
	s_addk_i32 s7, 0xff80
	s_lshl_b32 s7, s7, 3
	s_add_i32 s7, s7, s4
	s_addk_i32 s7, 0xc80
	s_movk_i32 s99, 0x1680
	s_cmpk_ge_i32 s7, 0x1880
	s_cbranch_scc1 .LBB0_1506
	v_and_b32_e32 v2, 63, v0
	v_lshlrev_b32_e32 v1, 3, v2
	v_and_b32_e32 v4, 56, v1
	v_lshlrev_b32_e32 v35, 1, v2
	v_lshlrev_b32_e32 v134, 8, v2
	v_ashrrev_i32_e32 v135, 3, v2
	v_lshlrev_b32_e32 v136, 4, v2
	s_lshl_b32 s6, s7, 7
	v_lshlrev_b32_e32 v2, 1, v4
	s_branch .LBB0_1498
